# attn task table cached in LDS (static LDS 5632 B above the dynamic region): per-task table lookup becomes a ds_read instead of a global load round trip
# speedup vs baseline: 1.0011x; 1.0011x over previous
.LBB0_214:
	s_and_b64 vcc, exec, s[4:5]
	s_cbranch_vccz .LBB0_359
	v_readlane_b32 s4, v254, 5
	s_mov_b32 s0, s4
	v_readlane_b32 s5, v254, 6
	v_writelane_b32 v254, s0, 5
	s_ashr_i32 s5, s4, 31
	s_lshl_b64 s[4:5], s[4:5], 2
	v_writelane_b32 v254, s1, 6
	s_nop 0
	v_readlane_b32 s10, v254, 7
	v_readlane_b32 s11, v254, 8
	s_load_dwordx2 s[8:9], s[10:11], 0x108
	s_waitcnt lgkmcnt(0)
	s_add_u32 s4, s8, s4
	s_addc_u32 s5, s9, s5
	v_writelane_b32 v254, s4, 14
	s_add_u32 s6, s8, 0x35a5000
	s_addc_u32 s7, s9, 0
	v_writelane_b32 v254, s5, 15
	v_writelane_b32 v254, s6, 16
	s_load_dwordx2 s[4:5], s[10:11], 0x98
	s_nop 0
	v_writelane_b32 v254, s7, 17
	s_add_u32 s6, s8, 0x11925000
	s_addc_u32 s7, s9, 0
	v_writelane_b32 v254, s6, 18
	s_nop 1
	v_writelane_b32 v254, s7, 19
	s_add_u32 s6, s8, 0x1525000
	s_addc_u32 s7, s9, 0
	v_writelane_b32 v254, s6, 20
	s_nop 1
	v_writelane_b32 v254, s7, 21
	s_nop 0
	v_readlane_b32 s6, v254, 11
	v_readlane_b32 s7, v254, 12
	s_mov_b32 s0, s6
	s_lshl_b32 s6, s6, 6
	s_ashr_i32 s7, s6, 31
	s_lshl_b64 s[6:7], s[6:7], 2
	s_waitcnt lgkmcnt(0)
	s_add_u32 s4, s4, s6
	s_addc_u32 s5, s5, s7
	v_writelane_b32 v254, s4, 22
	s_nop 1
	v_writelane_b32 v254, s5, 23
	s_add_u32 s4, s8, 0x1ac85000
	s_addc_u32 s5, s9, 0
	v_writelane_b32 v254, s4, 24
	s_nop 1
	v_writelane_b32 v254, s5, 25
	s_add_u32 s4, s8, 0x19385000
	s_addc_u32 s5, s9, 0
	v_writelane_b32 v254, s4, 26
	s_nop 1
	v_writelane_b32 v254, s5, 27
	s_add_u32 s4, s8, 0x1b4c5000
	s_addc_u32 s5, s9, 0
	v_writelane_b32 v254, s4, 28
	s_nop 1
	v_writelane_b32 v254, s5, 29
	s_add_u32 s4, s8, 0x19b85000
	s_addc_u32 s5, s9, 0
	v_writelane_b32 v254, s4, 30
	s_nop 1
	v_writelane_b32 v254, s5, 31
	s_add_u32 s4, s8, 0x1b0a5000
	s_addc_u32 s5, s9, 0
	v_writelane_b32 v254, s4, 32
	s_nop 1
	v_writelane_b32 v254, s5, 33
	s_add_u32 s4, s8, 0x19785000
	s_addc_u32 s5, s9, 0
	v_writelane_b32 v254, s4, 34
	s_nop 1
	v_writelane_b32 v254, s5, 35
	s_add_u32 s4, s8, 0x19285000
	s_addc_u32 s5, s9, 0
	v_writelane_b32 v254, s4, 36
	s_nop 1
	v_writelane_b32 v254, s5, 37
	s_add_u32 s4, s8, 0x1b5cd000
	s_addc_u32 s5, s9, 0
	v_writelane_b32 v254, s4, 38
	s_nop 1
	v_writelane_b32 v254, s5, 39
	s_add_u32 s4, s8, 0x1c64d000
	s_addc_u32 s5, s9, 0
	v_writelane_b32 v254, s4, 40
	s_nop 1
	v_writelane_b32 v254, s5, 41
	s_add_u32 s4, s8, 0x19c85000
	s_addc_u32 s5, s9, 0
	v_writelane_b32 v254, s4, 42
	s_nop 1
	v_writelane_b32 v254, s5, 43
	s_lshl_b32 s4, s0, 1
	s_ashr_i32 s5, s4, 31
	s_lshl_b64 s[4:5], s[4:5], 2
	s_add_u32 s4, s8, s4
	s_addc_u32 s5, s9, s5
	v_writelane_b32 v254, s4, 44
	s_nop 1
	v_writelane_b32 v254, s5, 45
	s_getpc_b64 s[4:5]
	s_add_u32 s4, s4, _ZL5g_tab@rel32@lo+8
	s_addc_u32 s5, s5, _ZL5g_tab@rel32@hi+16
	v_lshlrev_b32_e32 v217, 2, v216
	v_add_u32_e32 v218, 0x800, v217
	global_load_dword v219, v217, s[4:5]
	global_load_dword v220, v217, s[4:5] offset:2048
	v_add_u32_e32 v222, 0x24100, v217
	v_cmp_gt_u32_e32 vcc, 0x180, v216
	s_and_saveexec_b64 s[6:7], vcc
	global_load_dword v221, v218, s[4:5] offset:2048
	s_waitcnt vmcnt(0)
	ds_write_b32 v222, v221 offset:4096
	s_mov_b64 exec, s[6:7]
	s_waitcnt vmcnt(0)
	ds_write_b32 v222, v219
	ds_write_b32 v222, v220 offset:2048
	s_waitcnt lgkmcnt(0)
	s_mov_b64 s[4:5], 0
	s_branch .LBB0_219

.LBB0_223:
	s_or_b64 exec, exec, s[4:5]
	s_add_i32 s0, 0, 0x24000
	s_mov_b64 s[4:5], src_shared_base
	s_cmp_lg_u32 s0, -1
	s_cselect_b32 s0, s0, 0
	s_cselect_b32 s4, s5, 0
	v_mov_b32_e32 v4, s0
	v_mov_b32_e32 v5, s4
	s_waitcnt lgkmcnt(0)
	s_barrier
	ds_read_b32 v4, v4
	s_movk_i32 s0, 0x548
	s_mov_b64 s[4:5], -1
	s_waitcnt lgkmcnt(0)
	s_barrier
	v_cmp_gt_i32_e32 vcc, s0, v4
	s_mov_b64 s[6:7], exec
	v_writelane_b32 v254, s6, 48
	s_nop 1
	v_writelane_b32 v254, s7, 49
	s_and_b64 s[6:7], s[6:7], vcc
	s_mov_b64 exec, s[6:7]
	s_cbranch_execz .LBB0_218
	v_lshlrev_b32_e32 v5, 2, v4
	v_add_u32_e32 v5, 0x24100, v5
	ds_read_b32 v10, v5
	s_mov_b32 s0, 0x10000
	s_waitcnt lgkmcnt(0)
	v_cmp_gt_u32_e64 s[4:5], s0, v10
	s_nop 1
	v_writelane_b32 v254, s4, 50
	s_mov_b32 s0, 0xffff
	v_cmp_lt_u32_e64 s[6:7], s0, v10
	v_writelane_b32 v254, s5, 51
	v_cmp_ne_u32_sdwa s[4:5], v10, v206 src0_sel:WORD_1 src1_sel:DWORD
	v_writelane_b32 v254, s6, 52
	v_and_b32_e32 v12, 0xffff, v10
	s_and_b64 s[4:5], s[6:7], s[4:5]
	v_writelane_b32 v254, s7, 53
	s_and_saveexec_b64 s[6:7], s[4:5]
	s_xor_b64 s[6:7], exec, s[6:7]
	v_writelane_b32 v254, s6, 54
	s_nop 1
	v_writelane_b32 v254, s7, 55
	s_cbranch_execz .LBB0_314
	v_cmp_gt_i16_sdwa s[6:7], v10, v206 src0_sel:WORD_1 src1_sel:DWORD
	s_mov_b64 s[8:9], 0
	s_mov_b64 s[4:5], 0
	s_and_saveexec_b64 s[10:11], s[6:7]
	s_xor_b64 s[6:7], exec, s[10:11]
	s_cbranch_execz .LBB0_228
	v_mov_b32_e32 v0, 3
	v_cmp_ne_u16_sdwa s[4:5], v10, v0 src0_sel:WORD_1 src1_sel:DWORD
	s_and_b64 s[8:9], s[4:5], exec
	s_mov_b64 s[4:5], exec
	s_andn2_saveexec_b64 s[6:7], s[6:7]
	s_cbranch_execnz .LBB0_229

	.amdhsa_kernel _Z4mega6Params
		.amdhsa_group_segment_fixed_size 5632
		.amdhsa_private_segment_fixed_size 0
		.amdhsa_kernarg_size 536
		.amdhsa_user_sgpr_count 2
		.amdhsa_user_sgpr_dispatch_ptr 0
		.amdhsa_user_sgpr_queue_ptr 0
		.amdhsa_user_sgpr_kernarg_segment_ptr 1
		.amdhsa_user_sgpr_dispatch_id 0
		.amdhsa_user_sgpr_kernarg_preload_length 0
		.amdhsa_user_sgpr_kernarg_preload_offset 0
		.amdhsa_user_sgpr_private_segment_size 0
		.amdhsa_uses_dynamic_stack 0
		.amdhsa_enable_private_segment 0
		.amdhsa_system_sgpr_workgroup_id_x 1
		.amdhsa_system_sgpr_workgroup_id_y 0
		.amdhsa_system_sgpr_workgroup_id_z 0
		.amdhsa_system_sgpr_workgroup_info 0
		.amdhsa_system_vgpr_workitem_id 2
		.amdhsa_next_free_vgpr 256
		.amdhsa_next_free_sgpr 100
		.amdhsa_accum_offset 256
		.amdhsa_reserve_vcc 1
		.amdhsa_float_round_mode_32 0
		.amdhsa_float_round_mode_16_64 0
		.amdhsa_float_denorm_mode_32 3
		.amdhsa_float_denorm_mode_16_64 3
		.amdhsa_dx10_clamp 1
		.amdhsa_ieee_mode 1
		.amdhsa_fp16_overflow 0
		.amdhsa_tg_split 0
		.amdhsa_exception_fp_ieee_invalid_op 0
		.amdhsa_exception_fp_denorm_src 0
		.amdhsa_exception_fp_ieee_div_zero 0
		.amdhsa_exception_fp_ieee_overflow 0
		.amdhsa_exception_fp_ieee_underflow 0
		.amdhsa_exception_fp_ieee_inexact 0
		.amdhsa_exception_int_div_zero 0
	.end_amdhsa_kernel

amdhsa.kernels:
  - .agpr_count:     0
    .args:
      - .offset:         0
        .size:           280
        .value_kind:     by_value
      - .offset:         280
        .size:           4
        .value_kind:     hidden_block_count_x
      - .offset:         284
        .size:           4
        .value_kind:     hidden_block_count_y
      - .offset:         288
        .size:           4
        .value_kind:     hidden_block_count_z
      - .offset:         292
        .size:           2
        .value_kind:     hidden_group_size_x
      - .offset:         294
        .size:           2
        .value_kind:     hidden_group_size_y
      - .offset:         296
        .size:           2
        .value_kind:     hidden_group_size_z
      - .offset:         298
        .size:           2
        .value_kind:     hidden_remainder_x
      - .offset:         300
        .size:           2
        .value_kind:     hidden_remainder_y
      - .offset:         302
        .size:           2
        .value_kind:     hidden_remainder_z
      - .offset:         320
        .size:           8
        .value_kind:     hidden_global_offset_x
      - .offset:         328
        .size:           8
        .value_kind:     hidden_global_offset_y
      - .offset:         336
        .size:           8
        .value_kind:     hidden_global_offset_z
      - .offset:         344
        .size:           2
        .value_kind:     hidden_grid_dims
      - .offset:         368
        .size:           8
        .value_kind:     hidden_multigrid_sync_arg
      - .offset:         400
        .size:           4
        .value_kind:     hidden_dynamic_lds_size
    .group_segment_fixed_size: 5632
    .kernarg_segment_align: 8
    .kernarg_segment_size: 536
    .language:       OpenCL C
    .language_version:
      - 2
      - 0
    .max_flat_workgroup_size: 512
    .name:           _Z4mega6Params
    .private_segment_fixed_size: 0
    .sgpr_count:     106
    .sgpr_spill_count: 210
    .symbol:         _Z4mega6Params.kd
    .uniform_work_group_size: 1
    .uses_dynamic_stack: false
    .vgpr_count:     256
    .vgpr_spill_count: 0
    .wavefront_size: 64
